# phase 1 modulated norm rewritten (16 contiguous rows per wave, x loads 3 row-pairs ahead)
# speedup vs baseline: 1.0017x; 1.0017x over previous
.LBB0_97:
	s_nop 0
	s_mov_b64 s[0:1], 0

.LBB0_1055:
	s_cmp_gt_i32 s86, 0
	s_mov_b64 s[0:1], -1
	s_movk_i32 s50, 0x1000
	s_movk_i32 s56, 0x3000
	s_cbranch_scc0 .LBB0_1071
	s_waitcnt vmcnt(0) lgkmcnt(0)
	v_mov_b32_e32 v1, v163
	v_mov_b32_e32 v0, v163
	v_readlane_b32 s0, v250, 7
	v_ashrrev_i32_e32 v0, 6, v0
	s_nop 0
	v_add_u32_e32 v37, s0, v0
	s_movk_i32 s0, 0x4200
	v_cmp_gt_i32_e32 vcc, s0, v37
	s_mov_b64 s[2:3], exec
	v_readlane_b32 s12, v254, 22
	v_readlane_b32 s14, v254, 24
	v_readlane_b32 s15, v254, 25
	v_readlane_b32 s36, v249, 12
	s_and_b64 s[0:1], s[2:3], vcc
	v_readlane_b32 s13, v254, 23
	v_readlane_b32 s16, v254, 26
	v_readlane_b32 s17, v254, 27
	v_readlane_b32 s24, v254, 34
	v_readlane_b32 s25, v254, 35
	v_readlane_b32 s37, v249, 13
	v_readlane_b32 s38, v249, 14
	v_readlane_b32 s39, v249, 15
	v_readlane_b32 s8, v253, 63
	s_movk_i32 s9, 0x3fff
	s_mov_b32 s10, 0x3a800000
	s_mov_b64 s[14:15], 0x1800
	v_readlane_b32 s18, v254, 28
	v_readlane_b32 s19, v254, 29
	v_readlane_b32 s20, v254, 30
	v_readlane_b32 s21, v254, 31
	v_readlane_b32 s22, v254, 32
	v_readlane_b32 s23, v254, 33
	v_readlane_b32 s26, v254, 36
	v_readlane_b32 s27, v254, 37
	v_readlane_b32 s40, v249, 16
	v_readlane_b32 s41, v249, 17
	v_readlane_b32 s42, v249, 18
	v_readlane_b32 s43, v249, 19
	s_mov_b64 exec, s[0:1]
	s_cbranch_execz .LBB0_1059
	v_readlane_b32 s4, v249, 14
	v_readlane_b32 s5, v249, 15
	v_readlane_b32 s6, v254, 22
	v_readlane_b32 s7, v254, 23
	v_readlane_b32 s8, v254, 26
	v_readlane_b32 s9, v254, 27
	v_readlane_b32 s12, v254, 34
	v_readlane_b32 s13, v254, 35
	v_readlane_b32 s10, v250, 7
	v_readlane_b32 s14, v255, 4
	v_lshrrev_b32_e32 v184, 6, v163
	v_and_b32_e32 v190, 63, v163
	v_readfirstlane_b32 s24, v184
	v_lshlrev_b32_e32 v178, 5, v190
	v_lshlrev_b32_e32 v179, 4, v190
	v_xor_b32_e32 v172, 32, v190
	v_lshlrev_b32_e32 v172, 2, v172
	v_xor_b32_e32 v173, 16, v190
	v_lshlrev_b32_e32 v173, 2, v173
	v_xor_b32_e32 v174, 8, v190
	v_lshlrev_b32_e32 v174, 2, v174
	v_xor_b32_e32 v175, 4, v190
	v_lshlrev_b32_e32 v175, 2, v175
	v_xor_b32_e32 v176, 2, v190
	v_lshlrev_b32_e32 v176, 2, v176
	v_xor_b32_e32 v177, 1, v190
	v_lshlrev_b32_e32 v177, 2, v177
	s_add_u32 s10, s10, s24
	s_mov_b32 s25, s10
	s_cmp_lt_u32 s25, 0x800
	s_cbranch_scc0 .Lp1_ctx
.Lp1_group:
	s_lshr_b32 s24, s25, 9
	s_mul_i32 s24, s24, 0x6000
	s_add_u32 s20, s4, s24
	s_addc_u32 s21, s5, 0
	s_add_u32 s22, s20, 0x1000
	s_addc_u32 s23, s21, 0
	global_load_dwordx4 v[0:3], v178, s[12:13] offset:0
	global_load_dwordx4 v[16:19], v178, s[20:21] offset:0
	global_load_dwordx4 v[128:131], v178, s[22:23] offset:0
	global_load_dwordx4 v[4:7], v178, s[12:13] offset:16
	global_load_dwordx4 v[20:23], v178, s[20:21] offset:16
	global_load_dwordx4 v[132:135], v178, s[22:23] offset:16
	global_load_dwordx4 v[8:11], v178, s[12:13] offset:2048
	global_load_dwordx4 v[24:27], v178, s[20:21] offset:2048
	global_load_dwordx4 v[136:139], v178, s[22:23] offset:2048
	global_load_dwordx4 v[12:15], v178, s[12:13] offset:2064
	global_load_dwordx4 v[28:31], v178, s[20:21] offset:2064
	global_load_dwordx4 v[140:143], v178, s[22:23] offset:2064
	s_lshl_b32 s24, s25, 16
	s_add_u32 s16, s6, s24
	s_addc_u32 s17, s7, 0
	s_add_u32 s16, s16, 0x1000
	s_addc_u32 s17, s17, 0
	s_lshl_b32 s24, s25, 15
	s_add_u32 s24, s24, 0x4000800
	s_add_u32 s18, s4, s24
	s_addc_u32 s19, s5, 0
	global_load_dwordx4 v[32:35], v178, s[16:17] offset:-4096
	global_load_dwordx4 v[36:39], v178, s[16:17] offset:-4080
	global_load_dwordx4 v[40:43], v178, s[16:17] offset:-2048
	global_load_dwordx4 v[44:47], v178, s[16:17] offset:-2032
	global_load_dwordx4 v[48:51], v178, s[16:17] offset:0
	global_load_dwordx4 v[52:55], v178, s[16:17] offset:16
	global_load_dwordx4 v[56:59], v178, s[16:17] offset:2048
	global_load_dwordx4 v[60:63], v178, s[16:17] offset:2064
	s_add_u32 s16, s16, 0x2000
	s_addc_u32 s17, s17, 0
	global_load_dwordx4 v[64:67], v178, s[16:17] offset:-4096
	global_load_dwordx4 v[68:71], v178, s[16:17] offset:-4080
	global_load_dwordx4 v[72:75], v178, s[16:17] offset:-2048
	global_load_dwordx4 v[76:79], v178, s[16:17] offset:-2032
	global_load_dwordx4 v[80:83], v178, s[16:17] offset:0
	global_load_dwordx4 v[84:87], v178, s[16:17] offset:16
	global_load_dwordx4 v[88:91], v178, s[16:17] offset:2048
	global_load_dwordx4 v[92:95], v178, s[16:17] offset:2064
	s_add_u32 s16, s16, 0x2000
	s_addc_u32 s17, s17, 0
	global_load_dwordx4 v[96:99], v178, s[16:17] offset:-4096
	global_load_dwordx4 v[100:103], v178, s[16:17] offset:-4080
	global_load_dwordx4 v[104:107], v178, s[16:17] offset:-2048
	global_load_dwordx4 v[108:111], v178, s[16:17] offset:-2032
	global_load_dwordx4 v[112:115], v178, s[16:17] offset:0
	global_load_dwordx4 v[116:119], v178, s[16:17] offset:16
	global_load_dwordx4 v[120:123], v178, s[16:17] offset:2048
	global_load_dwordx4 v[124:127], v178, s[16:17] offset:2064
	s_waitcnt vmcnt(24)
	v_add_f32_e32 v128, 1.0, v128
	v_add_f32_e32 v129, 1.0, v129
	v_add_f32_e32 v130, 1.0, v130
	v_add_f32_e32 v131, 1.0, v131
	v_add_f32_e32 v132, 1.0, v132
	v_add_f32_e32 v133, 1.0, v133
	v_add_f32_e32 v134, 1.0, v134
	v_add_f32_e32 v135, 1.0, v135
	v_add_f32_e32 v136, 1.0, v136
	v_add_f32_e32 v137, 1.0, v137
	v_add_f32_e32 v138, 1.0, v138
	v_add_f32_e32 v139, 1.0, v139
	v_add_f32_e32 v140, 1.0, v140
	v_add_f32_e32 v141, 1.0, v141
	v_add_f32_e32 v142, 1.0, v142
	v_add_f32_e32 v143, 1.0, v143
	v_mul_f32_e32 v0, v0, v128
	v_mul_f32_e32 v1, v1, v129
	v_mul_f32_e32 v2, v2, v130
	v_mul_f32_e32 v3, v3, v131
	v_mul_f32_e32 v4, v4, v132
	v_mul_f32_e32 v5, v5, v133
	v_mul_f32_e32 v6, v6, v134
	v_mul_f32_e32 v7, v7, v135
	v_mul_f32_e32 v8, v8, v136
	v_mul_f32_e32 v9, v9, v137
	v_mul_f32_e32 v10, v10, v138
	v_mul_f32_e32 v11, v11, v139
	v_mul_f32_e32 v12, v12, v140
	v_mul_f32_e32 v13, v13, v141
	v_mul_f32_e32 v14, v14, v142
	v_mul_f32_e32 v15, v15, v143
	s_waitcnt vmcnt(16)
	v_pk_mul_f32 v[180:181], v[32:33], v[32:33]
	v_pk_mul_f32 v[182:183], v[48:49], v[48:49]
	v_pk_fma_f32 v[180:181], v[34:35], v[34:35], v[180:181]
	v_pk_fma_f32 v[182:183], v[50:51], v[50:51], v[182:183]
	v_pk_fma_f32 v[180:181], v[36:37], v[36:37], v[180:181]
	v_pk_fma_f32 v[182:183], v[52:53], v[52:53], v[182:183]
	v_pk_fma_f32 v[180:181], v[38:39], v[38:39], v[180:181]
	v_pk_fma_f32 v[182:183], v[54:55], v[54:55], v[182:183]
	v_pk_fma_f32 v[180:181], v[40:41], v[40:41], v[180:181]
	v_pk_fma_f32 v[182:183], v[56:57], v[56:57], v[182:183]
	v_pk_fma_f32 v[180:181], v[42:43], v[42:43], v[180:181]
	v_pk_fma_f32 v[182:183], v[58:59], v[58:59], v[182:183]
	v_pk_fma_f32 v[180:181], v[44:45], v[44:45], v[180:181]
	v_pk_fma_f32 v[182:183], v[60:61], v[60:61], v[182:183]
	v_pk_fma_f32 v[180:181], v[46:47], v[46:47], v[180:181]
	v_pk_fma_f32 v[182:183], v[62:63], v[62:63], v[182:183]
	v_add_f32_e32 v180, v180, v181
	v_add_f32_e32 v182, v182, v183
	ds_bpermute_b32 v184, v172, v180
	ds_bpermute_b32 v185, v172, v182
	s_waitcnt lgkmcnt(1)
	v_add_f32_e32 v180, v180, v184
	s_waitcnt lgkmcnt(0)
	v_add_f32_e32 v182, v182, v185
	ds_bpermute_b32 v184, v173, v180
	ds_bpermute_b32 v185, v173, v182
	s_waitcnt lgkmcnt(1)
	v_add_f32_e32 v180, v180, v184
	s_waitcnt lgkmcnt(0)
	v_add_f32_e32 v182, v182, v185
	ds_bpermute_b32 v184, v174, v180
	ds_bpermute_b32 v185, v174, v182
	s_waitcnt lgkmcnt(1)
	v_add_f32_e32 v180, v180, v184
	s_waitcnt lgkmcnt(0)
	v_add_f32_e32 v182, v182, v185
	ds_bpermute_b32 v184, v175, v180
	ds_bpermute_b32 v185, v175, v182
	s_waitcnt lgkmcnt(1)
	v_add_f32_e32 v180, v180, v184
	s_waitcnt lgkmcnt(0)
	v_add_f32_e32 v182, v182, v185
	ds_bpermute_b32 v184, v176, v180
	ds_bpermute_b32 v185, v176, v182
	s_waitcnt lgkmcnt(1)
	v_add_f32_e32 v180, v180, v184
	s_waitcnt lgkmcnt(0)
	v_add_f32_e32 v182, v182, v185
	ds_bpermute_b32 v184, v177, v180
	ds_bpermute_b32 v185, v177, v182
	s_waitcnt lgkmcnt(1)
	v_add_f32_e32 v180, v180, v184
	s_waitcnt lgkmcnt(0)
	v_add_f32_e32 v182, v182, v185
	v_mov_b32_e32 v184, 0x358637bd
	v_fmamk_f32 v180, v180, 0x3a800000, v184
	v_fmamk_f32 v182, v182, 0x3a800000, v184
	v_rsq_f32_e32 v186, v180
	v_rsq_f32_e32 v188, v182
	v_pk_mul_f32 v[32:33], v[32:33], v[186:187] op_sel_hi:[1,0]
	v_pk_mul_f32 v[34:35], v[34:35], v[186:187] op_sel_hi:[1,0]
	v_pk_mul_f32 v[36:37], v[36:37], v[186:187] op_sel_hi:[1,0]
	v_pk_mul_f32 v[38:39], v[38:39], v[186:187] op_sel_hi:[1,0]
	v_pk_mul_f32 v[40:41], v[40:41], v[186:187] op_sel_hi:[1,0]
	v_pk_mul_f32 v[42:43], v[42:43], v[186:187] op_sel_hi:[1,0]
	v_pk_mul_f32 v[44:45], v[44:45], v[186:187] op_sel_hi:[1,0]
	v_pk_mul_f32 v[46:47], v[46:47], v[186:187] op_sel_hi:[1,0]
	v_pk_mul_f32 v[48:49], v[48:49], v[188:189] op_sel_hi:[1,0]
	v_pk_mul_f32 v[50:51], v[50:51], v[188:189] op_sel_hi:[1,0]
	v_pk_mul_f32 v[52:53], v[52:53], v[188:189] op_sel_hi:[1,0]
	v_pk_mul_f32 v[54:55], v[54:55], v[188:189] op_sel_hi:[1,0]
	v_pk_mul_f32 v[56:57], v[56:57], v[188:189] op_sel_hi:[1,0]
	v_pk_mul_f32 v[58:59], v[58:59], v[188:189] op_sel_hi:[1,0]
	v_pk_mul_f32 v[60:61], v[60:61], v[188:189] op_sel_hi:[1,0]
	v_pk_mul_f32 v[62:63], v[62:63], v[188:189] op_sel_hi:[1,0]
	v_pk_fma_f32 v[32:33], v[32:33], v[0:1], v[16:17]
	v_pk_fma_f32 v[34:35], v[34:35], v[2:3], v[18:19]
	v_pk_fma_f32 v[36:37], v[36:37], v[4:5], v[20:21]
	v_pk_fma_f32 v[38:39], v[38:39], v[6:7], v[22:23]
	v_pk_fma_f32 v[40:41], v[40:41], v[8:9], v[24:25]
	v_pk_fma_f32 v[42:43], v[42:43], v[10:11], v[26:27]
	v_pk_fma_f32 v[44:45], v[44:45], v[12:13], v[28:29]
	v_pk_fma_f32 v[46:47], v[46:47], v[14:15], v[30:31]
	v_pk_fma_f32 v[48:49], v[48:49], v[0:1], v[16:17]
	v_pk_fma_f32 v[50:51], v[50:51], v[2:3], v[18:19]
	v_pk_fma_f32 v[52:53], v[52:53], v[4:5], v[20:21]
	v_pk_fma_f32 v[54:55], v[54:55], v[6:7], v[22:23]
	v_pk_fma_f32 v[56:57], v[56:57], v[8:9], v[24:25]
	v_pk_fma_f32 v[58:59], v[58:59], v[10:11], v[26:27]
	v_pk_fma_f32 v[60:61], v[60:61], v[12:13], v[28:29]
	v_pk_fma_f32 v[62:63], v[62:63], v[14:15], v[30:31]
	v_cvt_pk_bf16_f32 v144, v32, v33
	v_cvt_pk_bf16_f32 v145, v34, v35
	v_cvt_pk_bf16_f32 v146, v36, v37
	v_cvt_pk_bf16_f32 v147, v38, v39
	v_cvt_pk_bf16_f32 v148, v40, v41
	v_cvt_pk_bf16_f32 v149, v42, v43
	v_cvt_pk_bf16_f32 v150, v44, v45
	v_cvt_pk_bf16_f32 v151, v46, v47
	v_cvt_pk_bf16_f32 v164, v48, v49
	v_cvt_pk_bf16_f32 v165, v50, v51
	v_cvt_pk_bf16_f32 v166, v52, v53
	v_cvt_pk_bf16_f32 v167, v54, v55
	v_cvt_pk_bf16_f32 v168, v56, v57
	v_cvt_pk_bf16_f32 v169, v58, v59
	v_cvt_pk_bf16_f32 v170, v60, v61
	v_cvt_pk_bf16_f32 v171, v62, v63
	global_store_dwordx4 v179, v[144:147], s[18:19] offset:-2048
	global_store_dwordx4 v179, v[148:151], s[18:19] offset:-1024
	global_store_dwordx4 v179, v[164:167], s[18:19] offset:0
	global_store_dwordx4 v179, v[168:171], s[18:19] offset:1024
	s_add_u32 s16, s16, 0x2000
	s_addc_u32 s17, s17, 0
	global_load_dwordx4 v[32:35], v178, s[16:17] offset:-4096
	global_load_dwordx4 v[36:39], v178, s[16:17] offset:-4080
	global_load_dwordx4 v[40:43], v178, s[16:17] offset:-2048
	global_load_dwordx4 v[44:47], v178, s[16:17] offset:-2032
	global_load_dwordx4 v[48:51], v178, s[16:17] offset:0
	global_load_dwordx4 v[52:55], v178, s[16:17] offset:16
	global_load_dwordx4 v[56:59], v178, s[16:17] offset:2048
	global_load_dwordx4 v[60:63], v178, s[16:17] offset:2064
	s_waitcnt vmcnt(20)
	v_pk_mul_f32 v[180:181], v[64:65], v[64:65]
	v_pk_mul_f32 v[182:183], v[80:81], v[80:81]
	v_pk_fma_f32 v[180:181], v[66:67], v[66:67], v[180:181]
	v_pk_fma_f32 v[182:183], v[82:83], v[82:83], v[182:183]
	v_pk_fma_f32 v[180:181], v[68:69], v[68:69], v[180:181]
	v_pk_fma_f32 v[182:183], v[84:85], v[84:85], v[182:183]
	v_pk_fma_f32 v[180:181], v[70:71], v[70:71], v[180:181]
	v_pk_fma_f32 v[182:183], v[86:87], v[86:87], v[182:183]
	v_pk_fma_f32 v[180:181], v[72:73], v[72:73], v[180:181]
	v_pk_fma_f32 v[182:183], v[88:89], v[88:89], v[182:183]
	v_pk_fma_f32 v[180:181], v[74:75], v[74:75], v[180:181]
	v_pk_fma_f32 v[182:183], v[90:91], v[90:91], v[182:183]
	v_pk_fma_f32 v[180:181], v[76:77], v[76:77], v[180:181]
	v_pk_fma_f32 v[182:183], v[92:93], v[92:93], v[182:183]
	v_pk_fma_f32 v[180:181], v[78:79], v[78:79], v[180:181]
	v_pk_fma_f32 v[182:183], v[94:95], v[94:95], v[182:183]
	v_add_f32_e32 v180, v180, v181
	v_add_f32_e32 v182, v182, v183
	ds_bpermute_b32 v184, v172, v180
	ds_bpermute_b32 v185, v172, v182
	s_waitcnt lgkmcnt(1)
	v_add_f32_e32 v180, v180, v184
	s_waitcnt lgkmcnt(0)
	v_add_f32_e32 v182, v182, v185
	ds_bpermute_b32 v184, v173, v180
	ds_bpermute_b32 v185, v173, v182
	s_waitcnt lgkmcnt(1)
	v_add_f32_e32 v180, v180, v184
	s_waitcnt lgkmcnt(0)
	v_add_f32_e32 v182, v182, v185
	ds_bpermute_b32 v184, v174, v180
	ds_bpermute_b32 v185, v174, v182
	s_waitcnt lgkmcnt(1)
	v_add_f32_e32 v180, v180, v184
	s_waitcnt lgkmcnt(0)
	v_add_f32_e32 v182, v182, v185
	ds_bpermute_b32 v184, v175, v180
	ds_bpermute_b32 v185, v175, v182
	s_waitcnt lgkmcnt(1)
	v_add_f32_e32 v180, v180, v184
	s_waitcnt lgkmcnt(0)
	v_add_f32_e32 v182, v182, v185
	ds_bpermute_b32 v184, v176, v180
	ds_bpermute_b32 v185, v176, v182
	s_waitcnt lgkmcnt(1)
	v_add_f32_e32 v180, v180, v184
	s_waitcnt lgkmcnt(0)
	v_add_f32_e32 v182, v182, v185
	ds_bpermute_b32 v184, v177, v180
	ds_bpermute_b32 v185, v177, v182
	s_waitcnt lgkmcnt(1)
	v_add_f32_e32 v180, v180, v184
	s_waitcnt lgkmcnt(0)
	v_add_f32_e32 v182, v182, v185
	v_mov_b32_e32 v184, 0x358637bd
	v_fmamk_f32 v180, v180, 0x3a800000, v184
	v_fmamk_f32 v182, v182, 0x3a800000, v184
	v_rsq_f32_e32 v186, v180
	v_rsq_f32_e32 v188, v182
	v_pk_mul_f32 v[64:65], v[64:65], v[186:187] op_sel_hi:[1,0]
	v_pk_mul_f32 v[66:67], v[66:67], v[186:187] op_sel_hi:[1,0]
	v_pk_mul_f32 v[68:69], v[68:69], v[186:187] op_sel_hi:[1,0]
	v_pk_mul_f32 v[70:71], v[70:71], v[186:187] op_sel_hi:[1,0]
	v_pk_mul_f32 v[72:73], v[72:73], v[186:187] op_sel_hi:[1,0]
	v_pk_mul_f32 v[74:75], v[74:75], v[186:187] op_sel_hi:[1,0]
	v_pk_mul_f32 v[76:77], v[76:77], v[186:187] op_sel_hi:[1,0]
	v_pk_mul_f32 v[78:79], v[78:79], v[186:187] op_sel_hi:[1,0]
	v_pk_mul_f32 v[80:81], v[80:81], v[188:189] op_sel_hi:[1,0]
	v_pk_mul_f32 v[82:83], v[82:83], v[188:189] op_sel_hi:[1,0]
	v_pk_mul_f32 v[84:85], v[84:85], v[188:189] op_sel_hi:[1,0]
	v_pk_mul_f32 v[86:87], v[86:87], v[188:189] op_sel_hi:[1,0]
	v_pk_mul_f32 v[88:89], v[88:89], v[188:189] op_sel_hi:[1,0]
	v_pk_mul_f32 v[90:91], v[90:91], v[188:189] op_sel_hi:[1,0]
	v_pk_mul_f32 v[92:93], v[92:93], v[188:189] op_sel_hi:[1,0]
	v_pk_mul_f32 v[94:95], v[94:95], v[188:189] op_sel_hi:[1,0]
	v_pk_fma_f32 v[64:65], v[64:65], v[0:1], v[16:17]
	v_pk_fma_f32 v[66:67], v[66:67], v[2:3], v[18:19]
	v_pk_fma_f32 v[68:69], v[68:69], v[4:5], v[20:21]
	v_pk_fma_f32 v[70:71], v[70:71], v[6:7], v[22:23]
	v_pk_fma_f32 v[72:73], v[72:73], v[8:9], v[24:25]
	v_pk_fma_f32 v[74:75], v[74:75], v[10:11], v[26:27]
	v_pk_fma_f32 v[76:77], v[76:77], v[12:13], v[28:29]
	v_pk_fma_f32 v[78:79], v[78:79], v[14:15], v[30:31]
	v_pk_fma_f32 v[80:81], v[80:81], v[0:1], v[16:17]
	v_pk_fma_f32 v[82:83], v[82:83], v[2:3], v[18:19]
	v_pk_fma_f32 v[84:85], v[84:85], v[4:5], v[20:21]
	v_pk_fma_f32 v[86:87], v[86:87], v[6:7], v[22:23]
	v_pk_fma_f32 v[88:89], v[88:89], v[8:9], v[24:25]
	v_pk_fma_f32 v[90:91], v[90:91], v[10:11], v[26:27]
	v_pk_fma_f32 v[92:93], v[92:93], v[12:13], v[28:29]
	v_pk_fma_f32 v[94:95], v[94:95], v[14:15], v[30:31]
	v_cvt_pk_bf16_f32 v144, v64, v65
	v_cvt_pk_bf16_f32 v145, v66, v67
	v_cvt_pk_bf16_f32 v146, v68, v69
	v_cvt_pk_bf16_f32 v147, v70, v71
	v_cvt_pk_bf16_f32 v148, v72, v73
	v_cvt_pk_bf16_f32 v149, v74, v75
	v_cvt_pk_bf16_f32 v150, v76, v77
	v_cvt_pk_bf16_f32 v151, v78, v79
	v_cvt_pk_bf16_f32 v164, v80, v81
	v_cvt_pk_bf16_f32 v165, v82, v83
	v_cvt_pk_bf16_f32 v166, v84, v85
	v_cvt_pk_bf16_f32 v167, v86, v87
	v_cvt_pk_bf16_f32 v168, v88, v89
	v_cvt_pk_bf16_f32 v169, v90, v91
	v_cvt_pk_bf16_f32 v170, v92, v93
	v_cvt_pk_bf16_f32 v171, v94, v95
	s_add_u32 s18, s18, 0x1000
	s_addc_u32 s19, s19, 0
	global_store_dwordx4 v179, v[144:147], s[18:19] offset:-2048
	global_store_dwordx4 v179, v[148:151], s[18:19] offset:-1024
	global_store_dwordx4 v179, v[164:167], s[18:19] offset:0
	global_store_dwordx4 v179, v[168:171], s[18:19] offset:1024
	s_add_u32 s16, s16, 0x2000
	s_addc_u32 s17, s17, 0
	global_load_dwordx4 v[64:67], v178, s[16:17] offset:-4096
	global_load_dwordx4 v[68:71], v178, s[16:17] offset:-4080
	global_load_dwordx4 v[72:75], v178, s[16:17] offset:-2048
	global_load_dwordx4 v[76:79], v178, s[16:17] offset:-2032
	global_load_dwordx4 v[80:83], v178, s[16:17] offset:0
	global_load_dwordx4 v[84:87], v178, s[16:17] offset:16
	global_load_dwordx4 v[88:91], v178, s[16:17] offset:2048
	global_load_dwordx4 v[92:95], v178, s[16:17] offset:2064
	s_waitcnt vmcnt(24)
	v_pk_mul_f32 v[180:181], v[96:97], v[96:97]
	v_pk_mul_f32 v[182:183], v[112:113], v[112:113]
	v_pk_fma_f32 v[180:181], v[98:99], v[98:99], v[180:181]
	v_pk_fma_f32 v[182:183], v[114:115], v[114:115], v[182:183]
	v_pk_fma_f32 v[180:181], v[100:101], v[100:101], v[180:181]
	v_pk_fma_f32 v[182:183], v[116:117], v[116:117], v[182:183]
	v_pk_fma_f32 v[180:181], v[102:103], v[102:103], v[180:181]
	v_pk_fma_f32 v[182:183], v[118:119], v[118:119], v[182:183]
	v_pk_fma_f32 v[180:181], v[104:105], v[104:105], v[180:181]
	v_pk_fma_f32 v[182:183], v[120:121], v[120:121], v[182:183]
	v_pk_fma_f32 v[180:181], v[106:107], v[106:107], v[180:181]
	v_pk_fma_f32 v[182:183], v[122:123], v[122:123], v[182:183]
	v_pk_fma_f32 v[180:181], v[108:109], v[108:109], v[180:181]
	v_pk_fma_f32 v[182:183], v[124:125], v[124:125], v[182:183]
	v_pk_fma_f32 v[180:181], v[110:111], v[110:111], v[180:181]
	v_pk_fma_f32 v[182:183], v[126:127], v[126:127], v[182:183]
	v_add_f32_e32 v180, v180, v181
	v_add_f32_e32 v182, v182, v183
	ds_bpermute_b32 v184, v172, v180
	ds_bpermute_b32 v185, v172, v182
	s_waitcnt lgkmcnt(1)
	v_add_f32_e32 v180, v180, v184
	s_waitcnt lgkmcnt(0)
	v_add_f32_e32 v182, v182, v185
	ds_bpermute_b32 v184, v173, v180
	ds_bpermute_b32 v185, v173, v182
	s_waitcnt lgkmcnt(1)
	v_add_f32_e32 v180, v180, v184
	s_waitcnt lgkmcnt(0)
	v_add_f32_e32 v182, v182, v185
	ds_bpermute_b32 v184, v174, v180
	ds_bpermute_b32 v185, v174, v182
	s_waitcnt lgkmcnt(1)
	v_add_f32_e32 v180, v180, v184
	s_waitcnt lgkmcnt(0)
	v_add_f32_e32 v182, v182, v185
	ds_bpermute_b32 v184, v175, v180
	ds_bpermute_b32 v185, v175, v182
	s_waitcnt lgkmcnt(1)
	v_add_f32_e32 v180, v180, v184
	s_waitcnt lgkmcnt(0)
	v_add_f32_e32 v182, v182, v185
	ds_bpermute_b32 v184, v176, v180
	ds_bpermute_b32 v185, v176, v182
	s_waitcnt lgkmcnt(1)
	v_add_f32_e32 v180, v180, v184
	s_waitcnt lgkmcnt(0)
	v_add_f32_e32 v182, v182, v185
	ds_bpermute_b32 v184, v177, v180
	ds_bpermute_b32 v185, v177, v182
	s_waitcnt lgkmcnt(1)
	v_add_f32_e32 v180, v180, v184
	s_waitcnt lgkmcnt(0)
	v_add_f32_e32 v182, v182, v185
	v_mov_b32_e32 v184, 0x358637bd
	v_fmamk_f32 v180, v180, 0x3a800000, v184
	v_fmamk_f32 v182, v182, 0x3a800000, v184
	v_rsq_f32_e32 v186, v180
	v_rsq_f32_e32 v188, v182
	v_pk_mul_f32 v[96:97], v[96:97], v[186:187] op_sel_hi:[1,0]
	v_pk_mul_f32 v[98:99], v[98:99], v[186:187] op_sel_hi:[1,0]
	v_pk_mul_f32 v[100:101], v[100:101], v[186:187] op_sel_hi:[1,0]
	v_pk_mul_f32 v[102:103], v[102:103], v[186:187] op_sel_hi:[1,0]
	v_pk_mul_f32 v[104:105], v[104:105], v[186:187] op_sel_hi:[1,0]
	v_pk_mul_f32 v[106:107], v[106:107], v[186:187] op_sel_hi:[1,0]
	v_pk_mul_f32 v[108:109], v[108:109], v[186:187] op_sel_hi:[1,0]
	v_pk_mul_f32 v[110:111], v[110:111], v[186:187] op_sel_hi:[1,0]
	v_pk_mul_f32 v[112:113], v[112:113], v[188:189] op_sel_hi:[1,0]
	v_pk_mul_f32 v[114:115], v[114:115], v[188:189] op_sel_hi:[1,0]
	v_pk_mul_f32 v[116:117], v[116:117], v[188:189] op_sel_hi:[1,0]
	v_pk_mul_f32 v[118:119], v[118:119], v[188:189] op_sel_hi:[1,0]
	v_pk_mul_f32 v[120:121], v[120:121], v[188:189] op_sel_hi:[1,0]
	v_pk_mul_f32 v[122:123], v[122:123], v[188:189] op_sel_hi:[1,0]
	v_pk_mul_f32 v[124:125], v[124:125], v[188:189] op_sel_hi:[1,0]
	v_pk_mul_f32 v[126:127], v[126:127], v[188:189] op_sel_hi:[1,0]
	v_pk_fma_f32 v[96:97], v[96:97], v[0:1], v[16:17]
	v_pk_fma_f32 v[98:99], v[98:99], v[2:3], v[18:19]
	v_pk_fma_f32 v[100:101], v[100:101], v[4:5], v[20:21]
	v_pk_fma_f32 v[102:103], v[102:103], v[6:7], v[22:23]
	v_pk_fma_f32 v[104:105], v[104:105], v[8:9], v[24:25]
	v_pk_fma_f32 v[106:107], v[106:107], v[10:11], v[26:27]
	v_pk_fma_f32 v[108:109], v[108:109], v[12:13], v[28:29]
	v_pk_fma_f32 v[110:111], v[110:111], v[14:15], v[30:31]
	v_pk_fma_f32 v[112:113], v[112:113], v[0:1], v[16:17]
	v_pk_fma_f32 v[114:115], v[114:115], v[2:3], v[18:19]
	v_pk_fma_f32 v[116:117], v[116:117], v[4:5], v[20:21]
	v_pk_fma_f32 v[118:119], v[118:119], v[6:7], v[22:23]
	v_pk_fma_f32 v[120:121], v[120:121], v[8:9], v[24:25]
	v_pk_fma_f32 v[122:123], v[122:123], v[10:11], v[26:27]
	v_pk_fma_f32 v[124:125], v[124:125], v[12:13], v[28:29]
	v_pk_fma_f32 v[126:127], v[126:127], v[14:15], v[30:31]
	v_cvt_pk_bf16_f32 v144, v96, v97
	v_cvt_pk_bf16_f32 v145, v98, v99
	v_cvt_pk_bf16_f32 v146, v100, v101
	v_cvt_pk_bf16_f32 v147, v102, v103
	v_cvt_pk_bf16_f32 v148, v104, v105
	v_cvt_pk_bf16_f32 v149, v106, v107
	v_cvt_pk_bf16_f32 v150, v108, v109
	v_cvt_pk_bf16_f32 v151, v110, v111
	v_cvt_pk_bf16_f32 v164, v112, v113
	v_cvt_pk_bf16_f32 v165, v114, v115
	v_cvt_pk_bf16_f32 v166, v116, v117
	v_cvt_pk_bf16_f32 v167, v118, v119
	v_cvt_pk_bf16_f32 v168, v120, v121
	v_cvt_pk_bf16_f32 v169, v122, v123
	v_cvt_pk_bf16_f32 v170, v124, v125
	v_cvt_pk_bf16_f32 v171, v126, v127
	s_add_u32 s18, s18, 0x1000
	s_addc_u32 s19, s19, 0
	global_store_dwordx4 v179, v[144:147], s[18:19] offset:-2048
	global_store_dwordx4 v179, v[148:151], s[18:19] offset:-1024
	global_store_dwordx4 v179, v[164:167], s[18:19] offset:0
	global_store_dwordx4 v179, v[168:171], s[18:19] offset:1024
	s_add_u32 s16, s16, 0x2000
	s_addc_u32 s17, s17, 0
	global_load_dwordx4 v[96:99], v178, s[16:17] offset:-4096
	global_load_dwordx4 v[100:103], v178, s[16:17] offset:-4080
	global_load_dwordx4 v[104:107], v178, s[16:17] offset:-2048
	global_load_dwordx4 v[108:111], v178, s[16:17] offset:-2032
	global_load_dwordx4 v[112:115], v178, s[16:17] offset:0
	global_load_dwordx4 v[116:119], v178, s[16:17] offset:16
	global_load_dwordx4 v[120:123], v178, s[16:17] offset:2048
	global_load_dwordx4 v[124:127], v178, s[16:17] offset:2064
	s_waitcnt vmcnt(24)
	v_pk_mul_f32 v[180:181], v[32:33], v[32:33]
	v_pk_mul_f32 v[182:183], v[48:49], v[48:49]
	v_pk_fma_f32 v[180:181], v[34:35], v[34:35], v[180:181]
	v_pk_fma_f32 v[182:183], v[50:51], v[50:51], v[182:183]
	v_pk_fma_f32 v[180:181], v[36:37], v[36:37], v[180:181]
	v_pk_fma_f32 v[182:183], v[52:53], v[52:53], v[182:183]
	v_pk_fma_f32 v[180:181], v[38:39], v[38:39], v[180:181]
	v_pk_fma_f32 v[182:183], v[54:55], v[54:55], v[182:183]
	v_pk_fma_f32 v[180:181], v[40:41], v[40:41], v[180:181]
	v_pk_fma_f32 v[182:183], v[56:57], v[56:57], v[182:183]
	v_pk_fma_f32 v[180:181], v[42:43], v[42:43], v[180:181]
	v_pk_fma_f32 v[182:183], v[58:59], v[58:59], v[182:183]
	v_pk_fma_f32 v[180:181], v[44:45], v[44:45], v[180:181]
	v_pk_fma_f32 v[182:183], v[60:61], v[60:61], v[182:183]
	v_pk_fma_f32 v[180:181], v[46:47], v[46:47], v[180:181]
	v_pk_fma_f32 v[182:183], v[62:63], v[62:63], v[182:183]
	v_add_f32_e32 v180, v180, v181
	v_add_f32_e32 v182, v182, v183
	ds_bpermute_b32 v184, v172, v180
	ds_bpermute_b32 v185, v172, v182
	s_waitcnt lgkmcnt(1)
	v_add_f32_e32 v180, v180, v184
	s_waitcnt lgkmcnt(0)
	v_add_f32_e32 v182, v182, v185
	ds_bpermute_b32 v184, v173, v180
	ds_bpermute_b32 v185, v173, v182
	s_waitcnt lgkmcnt(1)
	v_add_f32_e32 v180, v180, v184
	s_waitcnt lgkmcnt(0)
	v_add_f32_e32 v182, v182, v185
	ds_bpermute_b32 v184, v174, v180
	ds_bpermute_b32 v185, v174, v182
	s_waitcnt lgkmcnt(1)
	v_add_f32_e32 v180, v180, v184
	s_waitcnt lgkmcnt(0)
	v_add_f32_e32 v182, v182, v185
	ds_bpermute_b32 v184, v175, v180
	ds_bpermute_b32 v185, v175, v182
	s_waitcnt lgkmcnt(1)
	v_add_f32_e32 v180, v180, v184
	s_waitcnt lgkmcnt(0)
	v_add_f32_e32 v182, v182, v185
	ds_bpermute_b32 v184, v176, v180
	ds_bpermute_b32 v185, v176, v182
	s_waitcnt lgkmcnt(1)
	v_add_f32_e32 v180, v180, v184
	s_waitcnt lgkmcnt(0)
	v_add_f32_e32 v182, v182, v185
	ds_bpermute_b32 v184, v177, v180
	ds_bpermute_b32 v185, v177, v182
	s_waitcnt lgkmcnt(1)
	v_add_f32_e32 v180, v180, v184
	s_waitcnt lgkmcnt(0)
	v_add_f32_e32 v182, v182, v185
	v_mov_b32_e32 v184, 0x358637bd
	v_fmamk_f32 v180, v180, 0x3a800000, v184
	v_fmamk_f32 v182, v182, 0x3a800000, v184
	v_rsq_f32_e32 v186, v180
	v_rsq_f32_e32 v188, v182
	v_pk_mul_f32 v[32:33], v[32:33], v[186:187] op_sel_hi:[1,0]
	v_pk_mul_f32 v[34:35], v[34:35], v[186:187] op_sel_hi:[1,0]
	v_pk_mul_f32 v[36:37], v[36:37], v[186:187] op_sel_hi:[1,0]
	v_pk_mul_f32 v[38:39], v[38:39], v[186:187] op_sel_hi:[1,0]
	v_pk_mul_f32 v[40:41], v[40:41], v[186:187] op_sel_hi:[1,0]
	v_pk_mul_f32 v[42:43], v[42:43], v[186:187] op_sel_hi:[1,0]
	v_pk_mul_f32 v[44:45], v[44:45], v[186:187] op_sel_hi:[1,0]
	v_pk_mul_f32 v[46:47], v[46:47], v[186:187] op_sel_hi:[1,0]
	v_pk_mul_f32 v[48:49], v[48:49], v[188:189] op_sel_hi:[1,0]
	v_pk_mul_f32 v[50:51], v[50:51], v[188:189] op_sel_hi:[1,0]
	v_pk_mul_f32 v[52:53], v[52:53], v[188:189] op_sel_hi:[1,0]
	v_pk_mul_f32 v[54:55], v[54:55], v[188:189] op_sel_hi:[1,0]
	v_pk_mul_f32 v[56:57], v[56:57], v[188:189] op_sel_hi:[1,0]
	v_pk_mul_f32 v[58:59], v[58:59], v[188:189] op_sel_hi:[1,0]
	v_pk_mul_f32 v[60:61], v[60:61], v[188:189] op_sel_hi:[1,0]
	v_pk_mul_f32 v[62:63], v[62:63], v[188:189] op_sel_hi:[1,0]
	v_pk_fma_f32 v[32:33], v[32:33], v[0:1], v[16:17]
	v_pk_fma_f32 v[34:35], v[34:35], v[2:3], v[18:19]
	v_pk_fma_f32 v[36:37], v[36:37], v[4:5], v[20:21]
	v_pk_fma_f32 v[38:39], v[38:39], v[6:7], v[22:23]
	v_pk_fma_f32 v[40:41], v[40:41], v[8:9], v[24:25]
	v_pk_fma_f32 v[42:43], v[42:43], v[10:11], v[26:27]
	v_pk_fma_f32 v[44:45], v[44:45], v[12:13], v[28:29]
	v_pk_fma_f32 v[46:47], v[46:47], v[14:15], v[30:31]
	v_pk_fma_f32 v[48:49], v[48:49], v[0:1], v[16:17]
	v_pk_fma_f32 v[50:51], v[50:51], v[2:3], v[18:19]
	v_pk_fma_f32 v[52:53], v[52:53], v[4:5], v[20:21]
	v_pk_fma_f32 v[54:55], v[54:55], v[6:7], v[22:23]
	v_pk_fma_f32 v[56:57], v[56:57], v[8:9], v[24:25]
	v_pk_fma_f32 v[58:59], v[58:59], v[10:11], v[26:27]
	v_pk_fma_f32 v[60:61], v[60:61], v[12:13], v[28:29]
	v_pk_fma_f32 v[62:63], v[62:63], v[14:15], v[30:31]
	v_cvt_pk_bf16_f32 v144, v32, v33
	v_cvt_pk_bf16_f32 v145, v34, v35
	v_cvt_pk_bf16_f32 v146, v36, v37
	v_cvt_pk_bf16_f32 v147, v38, v39
	v_cvt_pk_bf16_f32 v148, v40, v41
	v_cvt_pk_bf16_f32 v149, v42, v43
	v_cvt_pk_bf16_f32 v150, v44, v45
	v_cvt_pk_bf16_f32 v151, v46, v47
	v_cvt_pk_bf16_f32 v164, v48, v49
	v_cvt_pk_bf16_f32 v165, v50, v51
	v_cvt_pk_bf16_f32 v166, v52, v53
	v_cvt_pk_bf16_f32 v167, v54, v55
	v_cvt_pk_bf16_f32 v168, v56, v57
	v_cvt_pk_bf16_f32 v169, v58, v59
	v_cvt_pk_bf16_f32 v170, v60, v61
	v_cvt_pk_bf16_f32 v171, v62, v63
	s_add_u32 s18, s18, 0x1000
	s_addc_u32 s19, s19, 0
	global_store_dwordx4 v179, v[144:147], s[18:19] offset:-2048
	global_store_dwordx4 v179, v[148:151], s[18:19] offset:-1024
	global_store_dwordx4 v179, v[164:167], s[18:19] offset:0
	global_store_dwordx4 v179, v[168:171], s[18:19] offset:1024
	s_add_u32 s16, s16, 0x2000
	s_addc_u32 s17, s17, 0
	global_load_dwordx4 v[32:35], v178, s[16:17] offset:-4096
	global_load_dwordx4 v[36:39], v178, s[16:17] offset:-4080
	global_load_dwordx4 v[40:43], v178, s[16:17] offset:-2048
	global_load_dwordx4 v[44:47], v178, s[16:17] offset:-2032
	global_load_dwordx4 v[48:51], v178, s[16:17] offset:0
	global_load_dwordx4 v[52:55], v178, s[16:17] offset:16
	global_load_dwordx4 v[56:59], v178, s[16:17] offset:2048
	global_load_dwordx4 v[60:63], v178, s[16:17] offset:2064
	s_waitcnt vmcnt(24)
	v_pk_mul_f32 v[180:181], v[64:65], v[64:65]
	v_pk_mul_f32 v[182:183], v[80:81], v[80:81]
	v_pk_fma_f32 v[180:181], v[66:67], v[66:67], v[180:181]
	v_pk_fma_f32 v[182:183], v[82:83], v[82:83], v[182:183]
	v_pk_fma_f32 v[180:181], v[68:69], v[68:69], v[180:181]
	v_pk_fma_f32 v[182:183], v[84:85], v[84:85], v[182:183]
	v_pk_fma_f32 v[180:181], v[70:71], v[70:71], v[180:181]
	v_pk_fma_f32 v[182:183], v[86:87], v[86:87], v[182:183]
	v_pk_fma_f32 v[180:181], v[72:73], v[72:73], v[180:181]
	v_pk_fma_f32 v[182:183], v[88:89], v[88:89], v[182:183]
	v_pk_fma_f32 v[180:181], v[74:75], v[74:75], v[180:181]
	v_pk_fma_f32 v[182:183], v[90:91], v[90:91], v[182:183]
	v_pk_fma_f32 v[180:181], v[76:77], v[76:77], v[180:181]
	v_pk_fma_f32 v[182:183], v[92:93], v[92:93], v[182:183]
	v_pk_fma_f32 v[180:181], v[78:79], v[78:79], v[180:181]
	v_pk_fma_f32 v[182:183], v[94:95], v[94:95], v[182:183]
	v_add_f32_e32 v180, v180, v181
	v_add_f32_e32 v182, v182, v183
	ds_bpermute_b32 v184, v172, v180
	ds_bpermute_b32 v185, v172, v182
	s_waitcnt lgkmcnt(1)
	v_add_f32_e32 v180, v180, v184
	s_waitcnt lgkmcnt(0)
	v_add_f32_e32 v182, v182, v185
	ds_bpermute_b32 v184, v173, v180
	ds_bpermute_b32 v185, v173, v182
	s_waitcnt lgkmcnt(1)
	v_add_f32_e32 v180, v180, v184
	s_waitcnt lgkmcnt(0)
	v_add_f32_e32 v182, v182, v185
	ds_bpermute_b32 v184, v174, v180
	ds_bpermute_b32 v185, v174, v182
	s_waitcnt lgkmcnt(1)
	v_add_f32_e32 v180, v180, v184
	s_waitcnt lgkmcnt(0)
	v_add_f32_e32 v182, v182, v185
	ds_bpermute_b32 v184, v175, v180
	ds_bpermute_b32 v185, v175, v182
	s_waitcnt lgkmcnt(1)
	v_add_f32_e32 v180, v180, v184
	s_waitcnt lgkmcnt(0)
	v_add_f32_e32 v182, v182, v185
	ds_bpermute_b32 v184, v176, v180
	ds_bpermute_b32 v185, v176, v182
	s_waitcnt lgkmcnt(1)
	v_add_f32_e32 v180, v180, v184
	s_waitcnt lgkmcnt(0)
	v_add_f32_e32 v182, v182, v185
	ds_bpermute_b32 v184, v177, v180
	ds_bpermute_b32 v185, v177, v182
	s_waitcnt lgkmcnt(1)
	v_add_f32_e32 v180, v180, v184
	s_waitcnt lgkmcnt(0)
	v_add_f32_e32 v182, v182, v185
	v_mov_b32_e32 v184, 0x358637bd
	v_fmamk_f32 v180, v180, 0x3a800000, v184
	v_fmamk_f32 v182, v182, 0x3a800000, v184
	v_rsq_f32_e32 v186, v180
	v_rsq_f32_e32 v188, v182
	v_pk_mul_f32 v[64:65], v[64:65], v[186:187] op_sel_hi:[1,0]
	v_pk_mul_f32 v[66:67], v[66:67], v[186:187] op_sel_hi:[1,0]
	v_pk_mul_f32 v[68:69], v[68:69], v[186:187] op_sel_hi:[1,0]
	v_pk_mul_f32 v[70:71], v[70:71], v[186:187] op_sel_hi:[1,0]
	v_pk_mul_f32 v[72:73], v[72:73], v[186:187] op_sel_hi:[1,0]
	v_pk_mul_f32 v[74:75], v[74:75], v[186:187] op_sel_hi:[1,0]
	v_pk_mul_f32 v[76:77], v[76:77], v[186:187] op_sel_hi:[1,0]
	v_pk_mul_f32 v[78:79], v[78:79], v[186:187] op_sel_hi:[1,0]
	v_pk_mul_f32 v[80:81], v[80:81], v[188:189] op_sel_hi:[1,0]
	v_pk_mul_f32 v[82:83], v[82:83], v[188:189] op_sel_hi:[1,0]
	v_pk_mul_f32 v[84:85], v[84:85], v[188:189] op_sel_hi:[1,0]
	v_pk_mul_f32 v[86:87], v[86:87], v[188:189] op_sel_hi:[1,0]
	v_pk_mul_f32 v[88:89], v[88:89], v[188:189] op_sel_hi:[1,0]
	v_pk_mul_f32 v[90:91], v[90:91], v[188:189] op_sel_hi:[1,0]
	v_pk_mul_f32 v[92:93], v[92:93], v[188:189] op_sel_hi:[1,0]
	v_pk_mul_f32 v[94:95], v[94:95], v[188:189] op_sel_hi:[1,0]
	v_pk_fma_f32 v[64:65], v[64:65], v[0:1], v[16:17]
	v_pk_fma_f32 v[66:67], v[66:67], v[2:3], v[18:19]
	v_pk_fma_f32 v[68:69], v[68:69], v[4:5], v[20:21]
	v_pk_fma_f32 v[70:71], v[70:71], v[6:7], v[22:23]
	v_pk_fma_f32 v[72:73], v[72:73], v[8:9], v[24:25]
	v_pk_fma_f32 v[74:75], v[74:75], v[10:11], v[26:27]
	v_pk_fma_f32 v[76:77], v[76:77], v[12:13], v[28:29]
	v_pk_fma_f32 v[78:79], v[78:79], v[14:15], v[30:31]
	v_pk_fma_f32 v[80:81], v[80:81], v[0:1], v[16:17]
	v_pk_fma_f32 v[82:83], v[82:83], v[2:3], v[18:19]
	v_pk_fma_f32 v[84:85], v[84:85], v[4:5], v[20:21]
	v_pk_fma_f32 v[86:87], v[86:87], v[6:7], v[22:23]
	v_pk_fma_f32 v[88:89], v[88:89], v[8:9], v[24:25]
	v_pk_fma_f32 v[90:91], v[90:91], v[10:11], v[26:27]
	v_pk_fma_f32 v[92:93], v[92:93], v[12:13], v[28:29]
	v_pk_fma_f32 v[94:95], v[94:95], v[14:15], v[30:31]
	v_cvt_pk_bf16_f32 v144, v64, v65
	v_cvt_pk_bf16_f32 v145, v66, v67
	v_cvt_pk_bf16_f32 v146, v68, v69
	v_cvt_pk_bf16_f32 v147, v70, v71
	v_cvt_pk_bf16_f32 v148, v72, v73
	v_cvt_pk_bf16_f32 v149, v74, v75
	v_cvt_pk_bf16_f32 v150, v76, v77
	v_cvt_pk_bf16_f32 v151, v78, v79
	v_cvt_pk_bf16_f32 v164, v80, v81
	v_cvt_pk_bf16_f32 v165, v82, v83
	v_cvt_pk_bf16_f32 v166, v84, v85
	v_cvt_pk_bf16_f32 v167, v86, v87
	v_cvt_pk_bf16_f32 v168, v88, v89
	v_cvt_pk_bf16_f32 v169, v90, v91
	v_cvt_pk_bf16_f32 v170, v92, v93
	v_cvt_pk_bf16_f32 v171, v94, v95
	s_add_u32 s18, s18, 0x1000
	s_addc_u32 s19, s19, 0
	global_store_dwordx4 v179, v[144:147], s[18:19] offset:-2048
	global_store_dwordx4 v179, v[148:151], s[18:19] offset:-1024
	global_store_dwordx4 v179, v[164:167], s[18:19] offset:0
	global_store_dwordx4 v179, v[168:171], s[18:19] offset:1024
	s_add_u32 s16, s16, 0x2000
	s_addc_u32 s17, s17, 0
	global_load_dwordx4 v[64:67], v178, s[16:17] offset:-4096
	global_load_dwordx4 v[68:71], v178, s[16:17] offset:-4080
	global_load_dwordx4 v[72:75], v178, s[16:17] offset:-2048
	global_load_dwordx4 v[76:79], v178, s[16:17] offset:-2032
	global_load_dwordx4 v[80:83], v178, s[16:17] offset:0
	global_load_dwordx4 v[84:87], v178, s[16:17] offset:16
	global_load_dwordx4 v[88:91], v178, s[16:17] offset:2048
	global_load_dwordx4 v[92:95], v178, s[16:17] offset:2064
	s_waitcnt vmcnt(24)
	v_pk_mul_f32 v[180:181], v[96:97], v[96:97]
	v_pk_mul_f32 v[182:183], v[112:113], v[112:113]
	v_pk_fma_f32 v[180:181], v[98:99], v[98:99], v[180:181]
	v_pk_fma_f32 v[182:183], v[114:115], v[114:115], v[182:183]
	v_pk_fma_f32 v[180:181], v[100:101], v[100:101], v[180:181]
	v_pk_fma_f32 v[182:183], v[116:117], v[116:117], v[182:183]
	v_pk_fma_f32 v[180:181], v[102:103], v[102:103], v[180:181]
	v_pk_fma_f32 v[182:183], v[118:119], v[118:119], v[182:183]
	v_pk_fma_f32 v[180:181], v[104:105], v[104:105], v[180:181]
	v_pk_fma_f32 v[182:183], v[120:121], v[120:121], v[182:183]
	v_pk_fma_f32 v[180:181], v[106:107], v[106:107], v[180:181]
	v_pk_fma_f32 v[182:183], v[122:123], v[122:123], v[182:183]
	v_pk_fma_f32 v[180:181], v[108:109], v[108:109], v[180:181]
	v_pk_fma_f32 v[182:183], v[124:125], v[124:125], v[182:183]
	v_pk_fma_f32 v[180:181], v[110:111], v[110:111], v[180:181]
	v_pk_fma_f32 v[182:183], v[126:127], v[126:127], v[182:183]
	v_add_f32_e32 v180, v180, v181
	v_add_f32_e32 v182, v182, v183
	ds_bpermute_b32 v184, v172, v180
	ds_bpermute_b32 v185, v172, v182
	s_waitcnt lgkmcnt(1)
	v_add_f32_e32 v180, v180, v184
	s_waitcnt lgkmcnt(0)
	v_add_f32_e32 v182, v182, v185
	ds_bpermute_b32 v184, v173, v180
	ds_bpermute_b32 v185, v173, v182
	s_waitcnt lgkmcnt(1)
	v_add_f32_e32 v180, v180, v184
	s_waitcnt lgkmcnt(0)
	v_add_f32_e32 v182, v182, v185
	ds_bpermute_b32 v184, v174, v180
	ds_bpermute_b32 v185, v174, v182
	s_waitcnt lgkmcnt(1)
	v_add_f32_e32 v180, v180, v184
	s_waitcnt lgkmcnt(0)
	v_add_f32_e32 v182, v182, v185
	ds_bpermute_b32 v184, v175, v180
	ds_bpermute_b32 v185, v175, v182
	s_waitcnt lgkmcnt(1)
	v_add_f32_e32 v180, v180, v184
	s_waitcnt lgkmcnt(0)
	v_add_f32_e32 v182, v182, v185
	ds_bpermute_b32 v184, v176, v180
	ds_bpermute_b32 v185, v176, v182
	s_waitcnt lgkmcnt(1)
	v_add_f32_e32 v180, v180, v184
	s_waitcnt lgkmcnt(0)
	v_add_f32_e32 v182, v182, v185
	ds_bpermute_b32 v184, v177, v180
	ds_bpermute_b32 v185, v177, v182
	s_waitcnt lgkmcnt(1)
	v_add_f32_e32 v180, v180, v184
	s_waitcnt lgkmcnt(0)
	v_add_f32_e32 v182, v182, v185
	v_mov_b32_e32 v184, 0x358637bd
	v_fmamk_f32 v180, v180, 0x3a800000, v184
	v_fmamk_f32 v182, v182, 0x3a800000, v184
	v_rsq_f32_e32 v186, v180
	v_rsq_f32_e32 v188, v182
	v_pk_mul_f32 v[96:97], v[96:97], v[186:187] op_sel_hi:[1,0]
	v_pk_mul_f32 v[98:99], v[98:99], v[186:187] op_sel_hi:[1,0]
	v_pk_mul_f32 v[100:101], v[100:101], v[186:187] op_sel_hi:[1,0]
	v_pk_mul_f32 v[102:103], v[102:103], v[186:187] op_sel_hi:[1,0]
	v_pk_mul_f32 v[104:105], v[104:105], v[186:187] op_sel_hi:[1,0]
	v_pk_mul_f32 v[106:107], v[106:107], v[186:187] op_sel_hi:[1,0]
	v_pk_mul_f32 v[108:109], v[108:109], v[186:187] op_sel_hi:[1,0]
	v_pk_mul_f32 v[110:111], v[110:111], v[186:187] op_sel_hi:[1,0]
	v_pk_mul_f32 v[112:113], v[112:113], v[188:189] op_sel_hi:[1,0]
	v_pk_mul_f32 v[114:115], v[114:115], v[188:189] op_sel_hi:[1,0]
	v_pk_mul_f32 v[116:117], v[116:117], v[188:189] op_sel_hi:[1,0]
	v_pk_mul_f32 v[118:119], v[118:119], v[188:189] op_sel_hi:[1,0]
	v_pk_mul_f32 v[120:121], v[120:121], v[188:189] op_sel_hi:[1,0]
	v_pk_mul_f32 v[122:123], v[122:123], v[188:189] op_sel_hi:[1,0]
	v_pk_mul_f32 v[124:125], v[124:125], v[188:189] op_sel_hi:[1,0]
	v_pk_mul_f32 v[126:127], v[126:127], v[188:189] op_sel_hi:[1,0]
	v_pk_fma_f32 v[96:97], v[96:97], v[0:1], v[16:17]
	v_pk_fma_f32 v[98:99], v[98:99], v[2:3], v[18:19]
	v_pk_fma_f32 v[100:101], v[100:101], v[4:5], v[20:21]
	v_pk_fma_f32 v[102:103], v[102:103], v[6:7], v[22:23]
	v_pk_fma_f32 v[104:105], v[104:105], v[8:9], v[24:25]
	v_pk_fma_f32 v[106:107], v[106:107], v[10:11], v[26:27]
	v_pk_fma_f32 v[108:109], v[108:109], v[12:13], v[28:29]
	v_pk_fma_f32 v[110:111], v[110:111], v[14:15], v[30:31]
	v_pk_fma_f32 v[112:113], v[112:113], v[0:1], v[16:17]
	v_pk_fma_f32 v[114:115], v[114:115], v[2:3], v[18:19]
	v_pk_fma_f32 v[116:117], v[116:117], v[4:5], v[20:21]
	v_pk_fma_f32 v[118:119], v[118:119], v[6:7], v[22:23]
	v_pk_fma_f32 v[120:121], v[120:121], v[8:9], v[24:25]
	v_pk_fma_f32 v[122:123], v[122:123], v[10:11], v[26:27]
	v_pk_fma_f32 v[124:125], v[124:125], v[12:13], v[28:29]
	v_pk_fma_f32 v[126:127], v[126:127], v[14:15], v[30:31]
	v_cvt_pk_bf16_f32 v144, v96, v97
	v_cvt_pk_bf16_f32 v145, v98, v99
	v_cvt_pk_bf16_f32 v146, v100, v101
	v_cvt_pk_bf16_f32 v147, v102, v103
	v_cvt_pk_bf16_f32 v148, v104, v105
	v_cvt_pk_bf16_f32 v149, v106, v107
	v_cvt_pk_bf16_f32 v150, v108, v109
	v_cvt_pk_bf16_f32 v151, v110, v111
	v_cvt_pk_bf16_f32 v164, v112, v113
	v_cvt_pk_bf16_f32 v165, v114, v115
	v_cvt_pk_bf16_f32 v166, v116, v117
	v_cvt_pk_bf16_f32 v167, v118, v119
	v_cvt_pk_bf16_f32 v168, v120, v121
	v_cvt_pk_bf16_f32 v169, v122, v123
	v_cvt_pk_bf16_f32 v170, v124, v125
	v_cvt_pk_bf16_f32 v171, v126, v127
	s_add_u32 s18, s18, 0x1000
	s_addc_u32 s19, s19, 0
	global_store_dwordx4 v179, v[144:147], s[18:19] offset:-2048
	global_store_dwordx4 v179, v[148:151], s[18:19] offset:-1024
	global_store_dwordx4 v179, v[164:167], s[18:19] offset:0
	global_store_dwordx4 v179, v[168:171], s[18:19] offset:1024
	s_waitcnt vmcnt(16)
	v_pk_mul_f32 v[180:181], v[32:33], v[32:33]
	v_pk_mul_f32 v[182:183], v[48:49], v[48:49]
	v_pk_fma_f32 v[180:181], v[34:35], v[34:35], v[180:181]
	v_pk_fma_f32 v[182:183], v[50:51], v[50:51], v[182:183]
	v_pk_fma_f32 v[180:181], v[36:37], v[36:37], v[180:181]
	v_pk_fma_f32 v[182:183], v[52:53], v[52:53], v[182:183]
	v_pk_fma_f32 v[180:181], v[38:39], v[38:39], v[180:181]
	v_pk_fma_f32 v[182:183], v[54:55], v[54:55], v[182:183]
	v_pk_fma_f32 v[180:181], v[40:41], v[40:41], v[180:181]
	v_pk_fma_f32 v[182:183], v[56:57], v[56:57], v[182:183]
	v_pk_fma_f32 v[180:181], v[42:43], v[42:43], v[180:181]
	v_pk_fma_f32 v[182:183], v[58:59], v[58:59], v[182:183]
	v_pk_fma_f32 v[180:181], v[44:45], v[44:45], v[180:181]
	v_pk_fma_f32 v[182:183], v[60:61], v[60:61], v[182:183]
	v_pk_fma_f32 v[180:181], v[46:47], v[46:47], v[180:181]
	v_pk_fma_f32 v[182:183], v[62:63], v[62:63], v[182:183]
	v_add_f32_e32 v180, v180, v181
	v_add_f32_e32 v182, v182, v183
	ds_bpermute_b32 v184, v172, v180
	ds_bpermute_b32 v185, v172, v182
	s_waitcnt lgkmcnt(1)
	v_add_f32_e32 v180, v180, v184
	s_waitcnt lgkmcnt(0)
	v_add_f32_e32 v182, v182, v185
	ds_bpermute_b32 v184, v173, v180
	ds_bpermute_b32 v185, v173, v182
	s_waitcnt lgkmcnt(1)
	v_add_f32_e32 v180, v180, v184
	s_waitcnt lgkmcnt(0)
	v_add_f32_e32 v182, v182, v185
	ds_bpermute_b32 v184, v174, v180
	ds_bpermute_b32 v185, v174, v182
	s_waitcnt lgkmcnt(1)
	v_add_f32_e32 v180, v180, v184
	s_waitcnt lgkmcnt(0)
	v_add_f32_e32 v182, v182, v185
	ds_bpermute_b32 v184, v175, v180
	ds_bpermute_b32 v185, v175, v182
	s_waitcnt lgkmcnt(1)
	v_add_f32_e32 v180, v180, v184
	s_waitcnt lgkmcnt(0)
	v_add_f32_e32 v182, v182, v185
	ds_bpermute_b32 v184, v176, v180
	ds_bpermute_b32 v185, v176, v182
	s_waitcnt lgkmcnt(1)
	v_add_f32_e32 v180, v180, v184
	s_waitcnt lgkmcnt(0)
	v_add_f32_e32 v182, v182, v185
	ds_bpermute_b32 v184, v177, v180
	ds_bpermute_b32 v185, v177, v182
	s_waitcnt lgkmcnt(1)
	v_add_f32_e32 v180, v180, v184
	s_waitcnt lgkmcnt(0)
	v_add_f32_e32 v182, v182, v185
	v_mov_b32_e32 v184, 0x358637bd
	v_fmamk_f32 v180, v180, 0x3a800000, v184
	v_fmamk_f32 v182, v182, 0x3a800000, v184
	v_rsq_f32_e32 v186, v180
	v_rsq_f32_e32 v188, v182
	v_pk_mul_f32 v[32:33], v[32:33], v[186:187] op_sel_hi:[1,0]
	v_pk_mul_f32 v[34:35], v[34:35], v[186:187] op_sel_hi:[1,0]
	v_pk_mul_f32 v[36:37], v[36:37], v[186:187] op_sel_hi:[1,0]
	v_pk_mul_f32 v[38:39], v[38:39], v[186:187] op_sel_hi:[1,0]
	v_pk_mul_f32 v[40:41], v[40:41], v[186:187] op_sel_hi:[1,0]
	v_pk_mul_f32 v[42:43], v[42:43], v[186:187] op_sel_hi:[1,0]
	v_pk_mul_f32 v[44:45], v[44:45], v[186:187] op_sel_hi:[1,0]
	v_pk_mul_f32 v[46:47], v[46:47], v[186:187] op_sel_hi:[1,0]
	v_pk_mul_f32 v[48:49], v[48:49], v[188:189] op_sel_hi:[1,0]
	v_pk_mul_f32 v[50:51], v[50:51], v[188:189] op_sel_hi:[1,0]
	v_pk_mul_f32 v[52:53], v[52:53], v[188:189] op_sel_hi:[1,0]
	v_pk_mul_f32 v[54:55], v[54:55], v[188:189] op_sel_hi:[1,0]
	v_pk_mul_f32 v[56:57], v[56:57], v[188:189] op_sel_hi:[1,0]
	v_pk_mul_f32 v[58:59], v[58:59], v[188:189] op_sel_hi:[1,0]
	v_pk_mul_f32 v[60:61], v[60:61], v[188:189] op_sel_hi:[1,0]
	v_pk_mul_f32 v[62:63], v[62:63], v[188:189] op_sel_hi:[1,0]
	v_pk_fma_f32 v[32:33], v[32:33], v[0:1], v[16:17]
	v_pk_fma_f32 v[34:35], v[34:35], v[2:3], v[18:19]
	v_pk_fma_f32 v[36:37], v[36:37], v[4:5], v[20:21]
	v_pk_fma_f32 v[38:39], v[38:39], v[6:7], v[22:23]
	v_pk_fma_f32 v[40:41], v[40:41], v[8:9], v[24:25]
	v_pk_fma_f32 v[42:43], v[42:43], v[10:11], v[26:27]
	v_pk_fma_f32 v[44:45], v[44:45], v[12:13], v[28:29]
	v_pk_fma_f32 v[46:47], v[46:47], v[14:15], v[30:31]
	v_pk_fma_f32 v[48:49], v[48:49], v[0:1], v[16:17]
	v_pk_fma_f32 v[50:51], v[50:51], v[2:3], v[18:19]
	v_pk_fma_f32 v[52:53], v[52:53], v[4:5], v[20:21]
	v_pk_fma_f32 v[54:55], v[54:55], v[6:7], v[22:23]
	v_pk_fma_f32 v[56:57], v[56:57], v[8:9], v[24:25]
	v_pk_fma_f32 v[58:59], v[58:59], v[10:11], v[26:27]
	v_pk_fma_f32 v[60:61], v[60:61], v[12:13], v[28:29]
	v_pk_fma_f32 v[62:63], v[62:63], v[14:15], v[30:31]
	v_cvt_pk_bf16_f32 v144, v32, v33
	v_cvt_pk_bf16_f32 v145, v34, v35
	v_cvt_pk_bf16_f32 v146, v36, v37
	v_cvt_pk_bf16_f32 v147, v38, v39
	v_cvt_pk_bf16_f32 v148, v40, v41
	v_cvt_pk_bf16_f32 v149, v42, v43
	v_cvt_pk_bf16_f32 v150, v44, v45
	v_cvt_pk_bf16_f32 v151, v46, v47
	v_cvt_pk_bf16_f32 v164, v48, v49
	v_cvt_pk_bf16_f32 v165, v50, v51
	v_cvt_pk_bf16_f32 v166, v52, v53
	v_cvt_pk_bf16_f32 v167, v54, v55
	v_cvt_pk_bf16_f32 v168, v56, v57
	v_cvt_pk_bf16_f32 v169, v58, v59
	v_cvt_pk_bf16_f32 v170, v60, v61
	v_cvt_pk_bf16_f32 v171, v62, v63
	s_add_u32 s18, s18, 0x1000
	s_addc_u32 s19, s19, 0
	global_store_dwordx4 v179, v[144:147], s[18:19] offset:-2048
	global_store_dwordx4 v179, v[148:151], s[18:19] offset:-1024
	global_store_dwordx4 v179, v[164:167], s[18:19] offset:0
	global_store_dwordx4 v179, v[168:171], s[18:19] offset:1024
	s_waitcnt vmcnt(8)
	v_pk_mul_f32 v[180:181], v[64:65], v[64:65]
	v_pk_mul_f32 v[182:183], v[80:81], v[80:81]
	v_pk_fma_f32 v[180:181], v[66:67], v[66:67], v[180:181]
	v_pk_fma_f32 v[182:183], v[82:83], v[82:83], v[182:183]
	v_pk_fma_f32 v[180:181], v[68:69], v[68:69], v[180:181]
	v_pk_fma_f32 v[182:183], v[84:85], v[84:85], v[182:183]
	v_pk_fma_f32 v[180:181], v[70:71], v[70:71], v[180:181]
	v_pk_fma_f32 v[182:183], v[86:87], v[86:87], v[182:183]
	v_pk_fma_f32 v[180:181], v[72:73], v[72:73], v[180:181]
	v_pk_fma_f32 v[182:183], v[88:89], v[88:89], v[182:183]
	v_pk_fma_f32 v[180:181], v[74:75], v[74:75], v[180:181]
	v_pk_fma_f32 v[182:183], v[90:91], v[90:91], v[182:183]
	v_pk_fma_f32 v[180:181], v[76:77], v[76:77], v[180:181]
	v_pk_fma_f32 v[182:183], v[92:93], v[92:93], v[182:183]
	v_pk_fma_f32 v[180:181], v[78:79], v[78:79], v[180:181]
	v_pk_fma_f32 v[182:183], v[94:95], v[94:95], v[182:183]
	v_add_f32_e32 v180, v180, v181
	v_add_f32_e32 v182, v182, v183
	ds_bpermute_b32 v184, v172, v180
	ds_bpermute_b32 v185, v172, v182
	s_waitcnt lgkmcnt(1)
	v_add_f32_e32 v180, v180, v184
	s_waitcnt lgkmcnt(0)
	v_add_f32_e32 v182, v182, v185
	ds_bpermute_b32 v184, v173, v180
	ds_bpermute_b32 v185, v173, v182
	s_waitcnt lgkmcnt(1)
	v_add_f32_e32 v180, v180, v184
	s_waitcnt lgkmcnt(0)
	v_add_f32_e32 v182, v182, v185
	ds_bpermute_b32 v184, v174, v180
	ds_bpermute_b32 v185, v174, v182
	s_waitcnt lgkmcnt(1)
	v_add_f32_e32 v180, v180, v184
	s_waitcnt lgkmcnt(0)
	v_add_f32_e32 v182, v182, v185
	ds_bpermute_b32 v184, v175, v180
	ds_bpermute_b32 v185, v175, v182
	s_waitcnt lgkmcnt(1)
	v_add_f32_e32 v180, v180, v184
	s_waitcnt lgkmcnt(0)
	v_add_f32_e32 v182, v182, v185
	ds_bpermute_b32 v184, v176, v180
	ds_bpermute_b32 v185, v176, v182
	s_waitcnt lgkmcnt(1)
	v_add_f32_e32 v180, v180, v184
	s_waitcnt lgkmcnt(0)
	v_add_f32_e32 v182, v182, v185
	ds_bpermute_b32 v184, v177, v180
	ds_bpermute_b32 v185, v177, v182
	s_waitcnt lgkmcnt(1)
	v_add_f32_e32 v180, v180, v184
	s_waitcnt lgkmcnt(0)
	v_add_f32_e32 v182, v182, v185
	v_mov_b32_e32 v184, 0x358637bd
	v_fmamk_f32 v180, v180, 0x3a800000, v184
	v_fmamk_f32 v182, v182, 0x3a800000, v184
	v_rsq_f32_e32 v186, v180
	v_rsq_f32_e32 v188, v182
	v_pk_mul_f32 v[64:65], v[64:65], v[186:187] op_sel_hi:[1,0]
	v_pk_mul_f32 v[66:67], v[66:67], v[186:187] op_sel_hi:[1,0]
	v_pk_mul_f32 v[68:69], v[68:69], v[186:187] op_sel_hi:[1,0]
	v_pk_mul_f32 v[70:71], v[70:71], v[186:187] op_sel_hi:[1,0]
	v_pk_mul_f32 v[72:73], v[72:73], v[186:187] op_sel_hi:[1,0]
	v_pk_mul_f32 v[74:75], v[74:75], v[186:187] op_sel_hi:[1,0]
	v_pk_mul_f32 v[76:77], v[76:77], v[186:187] op_sel_hi:[1,0]
	v_pk_mul_f32 v[78:79], v[78:79], v[186:187] op_sel_hi:[1,0]
	v_pk_mul_f32 v[80:81], v[80:81], v[188:189] op_sel_hi:[1,0]
	v_pk_mul_f32 v[82:83], v[82:83], v[188:189] op_sel_hi:[1,0]
	v_pk_mul_f32 v[84:85], v[84:85], v[188:189] op_sel_hi:[1,0]
	v_pk_mul_f32 v[86:87], v[86:87], v[188:189] op_sel_hi:[1,0]
	v_pk_mul_f32 v[88:89], v[88:89], v[188:189] op_sel_hi:[1,0]
	v_pk_mul_f32 v[90:91], v[90:91], v[188:189] op_sel_hi:[1,0]
	v_pk_mul_f32 v[92:93], v[92:93], v[188:189] op_sel_hi:[1,0]
	v_pk_mul_f32 v[94:95], v[94:95], v[188:189] op_sel_hi:[1,0]
	v_pk_fma_f32 v[64:65], v[64:65], v[0:1], v[16:17]
	v_pk_fma_f32 v[66:67], v[66:67], v[2:3], v[18:19]
	v_pk_fma_f32 v[68:69], v[68:69], v[4:5], v[20:21]
	v_pk_fma_f32 v[70:71], v[70:71], v[6:7], v[22:23]
	v_pk_fma_f32 v[72:73], v[72:73], v[8:9], v[24:25]
	v_pk_fma_f32 v[74:75], v[74:75], v[10:11], v[26:27]
	v_pk_fma_f32 v[76:77], v[76:77], v[12:13], v[28:29]
	v_pk_fma_f32 v[78:79], v[78:79], v[14:15], v[30:31]
	v_pk_fma_f32 v[80:81], v[80:81], v[0:1], v[16:17]
	v_pk_fma_f32 v[82:83], v[82:83], v[2:3], v[18:19]
	v_pk_fma_f32 v[84:85], v[84:85], v[4:5], v[20:21]
	v_pk_fma_f32 v[86:87], v[86:87], v[6:7], v[22:23]
	v_pk_fma_f32 v[88:89], v[88:89], v[8:9], v[24:25]
	v_pk_fma_f32 v[90:91], v[90:91], v[10:11], v[26:27]
	v_pk_fma_f32 v[92:93], v[92:93], v[12:13], v[28:29]
	v_pk_fma_f32 v[94:95], v[94:95], v[14:15], v[30:31]
	v_cvt_pk_bf16_f32 v144, v64, v65
	v_cvt_pk_bf16_f32 v145, v66, v67
	v_cvt_pk_bf16_f32 v146, v68, v69
	v_cvt_pk_bf16_f32 v147, v70, v71
	v_cvt_pk_bf16_f32 v148, v72, v73
	v_cvt_pk_bf16_f32 v149, v74, v75
	v_cvt_pk_bf16_f32 v150, v76, v77
	v_cvt_pk_bf16_f32 v151, v78, v79
	v_cvt_pk_bf16_f32 v164, v80, v81
	v_cvt_pk_bf16_f32 v165, v82, v83
	v_cvt_pk_bf16_f32 v166, v84, v85
	v_cvt_pk_bf16_f32 v167, v86, v87
	v_cvt_pk_bf16_f32 v168, v88, v89
	v_cvt_pk_bf16_f32 v169, v90, v91
	v_cvt_pk_bf16_f32 v170, v92, v93
	v_cvt_pk_bf16_f32 v171, v94, v95
	s_add_u32 s18, s18, 0x1000
	s_addc_u32 s19, s19, 0
	global_store_dwordx4 v179, v[144:147], s[18:19] offset:-2048
	global_store_dwordx4 v179, v[148:151], s[18:19] offset:-1024
	global_store_dwordx4 v179, v[164:167], s[18:19] offset:0
	global_store_dwordx4 v179, v[168:171], s[18:19] offset:1024
	s_add_u32 s25, s25, s14
	s_cmp_lt_u32 s25, 0x800
	s_cbranch_scc1 .Lp1_group
.Lp1_ctx:
	s_cmp_lt_u32 s10, 0x200
	s_cbranch_scc0 .Lp1_done
.Lp1_cpair:
	s_add_u32 s20, s4, 0x18000
	s_addc_u32 s21, s5, 0
	s_add_u32 s22, s20, 0x1000
	s_addc_u32 s23, s21, 0
	global_load_dwordx4 v[0:3], v178, s[12:13] offset:0
	global_load_dwordx4 v[16:19], v178, s[20:21] offset:0
	global_load_dwordx4 v[128:131], v178, s[22:23] offset:0
	global_load_dwordx4 v[4:7], v178, s[12:13] offset:16
	global_load_dwordx4 v[20:23], v178, s[20:21] offset:16
	global_load_dwordx4 v[132:135], v178, s[22:23] offset:16
	global_load_dwordx4 v[8:11], v178, s[12:13] offset:2048
	global_load_dwordx4 v[24:27], v178, s[20:21] offset:2048
	global_load_dwordx4 v[136:139], v178, s[22:23] offset:2048
	global_load_dwordx4 v[12:15], v178, s[12:13] offset:2064
	global_load_dwordx4 v[28:31], v178, s[20:21] offset:2064
	global_load_dwordx4 v[140:143], v178, s[22:23] offset:2064
	s_lshl_b32 s24, s10, 13
	s_add_u32 s16, s8, s24
	s_addc_u32 s17, s9, 0
	s_add_u32 s16, s16, 0x1000
	s_addc_u32 s17, s17, 0
	s_lshl_b32 s24, s10, 12
	s_add_u32 s24, s24, 0x1C000800
	s_add_u32 s18, s4, s24
	s_addc_u32 s19, s5, 0
	global_load_dwordx4 v[32:35], v178, s[16:17] offset:-4096
	global_load_dwordx4 v[36:39], v178, s[16:17] offset:-4080
	global_load_dwordx4 v[40:43], v178, s[16:17] offset:-2048
	global_load_dwordx4 v[44:47], v178, s[16:17] offset:-2032
	global_load_dwordx4 v[48:51], v178, s[16:17] offset:0
	global_load_dwordx4 v[52:55], v178, s[16:17] offset:16
	global_load_dwordx4 v[56:59], v178, s[16:17] offset:2048
	global_load_dwordx4 v[60:63], v178, s[16:17] offset:2064
	s_waitcnt vmcnt(8)
	v_add_f32_e32 v128, 1.0, v128
	v_add_f32_e32 v129, 1.0, v129
	v_add_f32_e32 v130, 1.0, v130
	v_add_f32_e32 v131, 1.0, v131
	v_add_f32_e32 v132, 1.0, v132
	v_add_f32_e32 v133, 1.0, v133
	v_add_f32_e32 v134, 1.0, v134
	v_add_f32_e32 v135, 1.0, v135
	v_add_f32_e32 v136, 1.0, v136
	v_add_f32_e32 v137, 1.0, v137
	v_add_f32_e32 v138, 1.0, v138
	v_add_f32_e32 v139, 1.0, v139
	v_add_f32_e32 v140, 1.0, v140
	v_add_f32_e32 v141, 1.0, v141
	v_add_f32_e32 v142, 1.0, v142
	v_add_f32_e32 v143, 1.0, v143
	v_mul_f32_e32 v0, v0, v128
	v_mul_f32_e32 v1, v1, v129
	v_mul_f32_e32 v2, v2, v130
	v_mul_f32_e32 v3, v3, v131
	v_mul_f32_e32 v4, v4, v132
	v_mul_f32_e32 v5, v5, v133
	v_mul_f32_e32 v6, v6, v134
	v_mul_f32_e32 v7, v7, v135
	v_mul_f32_e32 v8, v8, v136
	v_mul_f32_e32 v9, v9, v137
	v_mul_f32_e32 v10, v10, v138
	v_mul_f32_e32 v11, v11, v139
	v_mul_f32_e32 v12, v12, v140
	v_mul_f32_e32 v13, v13, v141
	v_mul_f32_e32 v14, v14, v142
	v_mul_f32_e32 v15, v15, v143
	s_waitcnt vmcnt(0)
	v_pk_mul_f32 v[180:181], v[32:33], v[32:33]
	v_pk_mul_f32 v[182:183], v[48:49], v[48:49]
	v_pk_fma_f32 v[180:181], v[34:35], v[34:35], v[180:181]
	v_pk_fma_f32 v[182:183], v[50:51], v[50:51], v[182:183]
	v_pk_fma_f32 v[180:181], v[36:37], v[36:37], v[180:181]
	v_pk_fma_f32 v[182:183], v[52:53], v[52:53], v[182:183]
	v_pk_fma_f32 v[180:181], v[38:39], v[38:39], v[180:181]
	v_pk_fma_f32 v[182:183], v[54:55], v[54:55], v[182:183]
	v_pk_fma_f32 v[180:181], v[40:41], v[40:41], v[180:181]
	v_pk_fma_f32 v[182:183], v[56:57], v[56:57], v[182:183]
	v_pk_fma_f32 v[180:181], v[42:43], v[42:43], v[180:181]
	v_pk_fma_f32 v[182:183], v[58:59], v[58:59], v[182:183]
	v_pk_fma_f32 v[180:181], v[44:45], v[44:45], v[180:181]
	v_pk_fma_f32 v[182:183], v[60:61], v[60:61], v[182:183]
	v_pk_fma_f32 v[180:181], v[46:47], v[46:47], v[180:181]
	v_pk_fma_f32 v[182:183], v[62:63], v[62:63], v[182:183]
	v_add_f32_e32 v180, v180, v181
	v_add_f32_e32 v182, v182, v183
	ds_bpermute_b32 v184, v172, v180
	ds_bpermute_b32 v185, v172, v182
	s_waitcnt lgkmcnt(1)
	v_add_f32_e32 v180, v180, v184
	s_waitcnt lgkmcnt(0)
	v_add_f32_e32 v182, v182, v185
	ds_bpermute_b32 v184, v173, v180
	ds_bpermute_b32 v185, v173, v182
	s_waitcnt lgkmcnt(1)
	v_add_f32_e32 v180, v180, v184
	s_waitcnt lgkmcnt(0)
	v_add_f32_e32 v182, v182, v185
	ds_bpermute_b32 v184, v174, v180
	ds_bpermute_b32 v185, v174, v182
	s_waitcnt lgkmcnt(1)
	v_add_f32_e32 v180, v180, v184
	s_waitcnt lgkmcnt(0)
	v_add_f32_e32 v182, v182, v185
	ds_bpermute_b32 v184, v175, v180
	ds_bpermute_b32 v185, v175, v182
	s_waitcnt lgkmcnt(1)
	v_add_f32_e32 v180, v180, v184
	s_waitcnt lgkmcnt(0)
	v_add_f32_e32 v182, v182, v185
	ds_bpermute_b32 v184, v176, v180
	ds_bpermute_b32 v185, v176, v182
	s_waitcnt lgkmcnt(1)
	v_add_f32_e32 v180, v180, v184
	s_waitcnt lgkmcnt(0)
	v_add_f32_e32 v182, v182, v185
	ds_bpermute_b32 v184, v177, v180
	ds_bpermute_b32 v185, v177, v182
	s_waitcnt lgkmcnt(1)
	v_add_f32_e32 v180, v180, v184
	s_waitcnt lgkmcnt(0)
	v_add_f32_e32 v182, v182, v185
	v_mov_b32_e32 v184, 0x358637bd
	v_fmamk_f32 v180, v180, 0x3a800000, v184
	v_fmamk_f32 v182, v182, 0x3a800000, v184
	v_rsq_f32_e32 v186, v180
	v_rsq_f32_e32 v188, v182
	v_pk_mul_f32 v[32:33], v[32:33], v[186:187] op_sel_hi:[1,0]
	v_pk_mul_f32 v[34:35], v[34:35], v[186:187] op_sel_hi:[1,0]
	v_pk_mul_f32 v[36:37], v[36:37], v[186:187] op_sel_hi:[1,0]
	v_pk_mul_f32 v[38:39], v[38:39], v[186:187] op_sel_hi:[1,0]
	v_pk_mul_f32 v[40:41], v[40:41], v[186:187] op_sel_hi:[1,0]
	v_pk_mul_f32 v[42:43], v[42:43], v[186:187] op_sel_hi:[1,0]
	v_pk_mul_f32 v[44:45], v[44:45], v[186:187] op_sel_hi:[1,0]
	v_pk_mul_f32 v[46:47], v[46:47], v[186:187] op_sel_hi:[1,0]
	v_pk_mul_f32 v[48:49], v[48:49], v[188:189] op_sel_hi:[1,0]
	v_pk_mul_f32 v[50:51], v[50:51], v[188:189] op_sel_hi:[1,0]
	v_pk_mul_f32 v[52:53], v[52:53], v[188:189] op_sel_hi:[1,0]
	v_pk_mul_f32 v[54:55], v[54:55], v[188:189] op_sel_hi:[1,0]
	v_pk_mul_f32 v[56:57], v[56:57], v[188:189] op_sel_hi:[1,0]
	v_pk_mul_f32 v[58:59], v[58:59], v[188:189] op_sel_hi:[1,0]
	v_pk_mul_f32 v[60:61], v[60:61], v[188:189] op_sel_hi:[1,0]
	v_pk_mul_f32 v[62:63], v[62:63], v[188:189] op_sel_hi:[1,0]
	v_pk_fma_f32 v[32:33], v[32:33], v[0:1], v[16:17]
	v_pk_fma_f32 v[34:35], v[34:35], v[2:3], v[18:19]
	v_pk_fma_f32 v[36:37], v[36:37], v[4:5], v[20:21]
	v_pk_fma_f32 v[38:39], v[38:39], v[6:7], v[22:23]
	v_pk_fma_f32 v[40:41], v[40:41], v[8:9], v[24:25]
	v_pk_fma_f32 v[42:43], v[42:43], v[10:11], v[26:27]
	v_pk_fma_f32 v[44:45], v[44:45], v[12:13], v[28:29]
	v_pk_fma_f32 v[46:47], v[46:47], v[14:15], v[30:31]
	v_pk_fma_f32 v[48:49], v[48:49], v[0:1], v[16:17]
	v_pk_fma_f32 v[50:51], v[50:51], v[2:3], v[18:19]
	v_pk_fma_f32 v[52:53], v[52:53], v[4:5], v[20:21]
	v_pk_fma_f32 v[54:55], v[54:55], v[6:7], v[22:23]
	v_pk_fma_f32 v[56:57], v[56:57], v[8:9], v[24:25]
	v_pk_fma_f32 v[58:59], v[58:59], v[10:11], v[26:27]
	v_pk_fma_f32 v[60:61], v[60:61], v[12:13], v[28:29]
	v_pk_fma_f32 v[62:63], v[62:63], v[14:15], v[30:31]
	v_cvt_pk_bf16_f32 v144, v32, v33
	v_cvt_pk_bf16_f32 v145, v34, v35
	v_cvt_pk_bf16_f32 v146, v36, v37
	v_cvt_pk_bf16_f32 v147, v38, v39
	v_cvt_pk_bf16_f32 v148, v40, v41
	v_cvt_pk_bf16_f32 v149, v42, v43
	v_cvt_pk_bf16_f32 v150, v44, v45
	v_cvt_pk_bf16_f32 v151, v46, v47
	v_cvt_pk_bf16_f32 v164, v48, v49
	v_cvt_pk_bf16_f32 v165, v50, v51
	v_cvt_pk_bf16_f32 v166, v52, v53
	v_cvt_pk_bf16_f32 v167, v54, v55
	v_cvt_pk_bf16_f32 v168, v56, v57
	v_cvt_pk_bf16_f32 v169, v58, v59
	v_cvt_pk_bf16_f32 v170, v60, v61
	v_cvt_pk_bf16_f32 v171, v62, v63
	global_store_dwordx4 v179, v[144:147], s[18:19] offset:-2048
	global_store_dwordx4 v179, v[148:151], s[18:19] offset:-1024
	global_store_dwordx4 v179, v[164:167], s[18:19] offset:0
	global_store_dwordx4 v179, v[168:171], s[18:19] offset:1024
	s_add_u32 s10, s10, s14
	s_cmp_lt_u32 s10, 0x200
	s_cbranch_scc1 .Lp1_cpair
.Lp1_done:
.LBB0_1059:
	s_or_b64 exec, exec, s[2:3]
	v_mov_b32_e32 v0, v163
	v_mov_b32_e32 v1, v163
	v_readlane_b32 s0, v250, 7
	v_ashrrev_i32_e32 v2, 6, v1
	s_nop 0
	v_add_u32_e32 v46, s0, v2
	s_movk_i32 s0, 0x580
	v_cmp_gt_i32_e32 vcc, s0, v46
	s_and_saveexec_b64 s[0:1], vcc
	v_readlane_b32 s36, v251, 28
	v_readlane_b32 s37, v251, 29
	s_cbranch_execz .LBB0_1070
	v_lshrrev_b32_e32 v1, 6, v1
	v_lshlrev_b32_e32 v0, 2, v0
	v_readlane_b32 s2, v250, 7
	v_and_b32_e32 v47, 0xfc, v0
	s_nop 0
	v_add_u16_e32 v48, s2, v1
	s_mov_b64 s[2:3], 0
